# gemm_small fragment stream: k permutation so a 4-lane group reads a full 128B line per stage pair (same k for A and B fragments)
# speedup vs baseline: 1.0311x; 1.0029x over previous
.LBB0_704:
	s_and_b32 s18, s22, 0xffffffc0
	v_or_b32_e32 v2, s18, v174
	v_lshlrev_b32_e32 v4, 1, v2
	v_or_b32_e32 v5, 0x60, v4
	v_mov_b64_e32 v[0:1], s[8:9]
	v_mad_u64_u32 v[64:65], s[18:19], s61, v5, v[0:1]
	v_or_b32_e32 v5, 64, v4
	v_or_b32_e32 v4, 32, v4
	v_mad_u64_u32 v[66:67], s[18:19], s61, v5, v[0:1]
	v_mad_u64_u32 v[68:69], s[18:19], s61, v4, v[0:1]
	v_mad_i64_i32 v[70:71], s[18:19], s21, v2, v[0:1]
	s_lshl_b32 s18, s23, 6
	s_and_b32 s18, s18, 0x3c0
	v_or_b32_e32 v0, s18, v174
	v_mul_u32_u24_e32 v152, s61, v0
	v_lshl_add_u64 v[0:1], s[4:5], 0, v[152:153]
	v_lshlrev_b64 v[0:1], 1, v[0:1]
	v_ashrrev_i32_e32 v3, 31, v2
	v_lshl_add_u64 v[72:73], s[10:11], 0, v[0:1]
	v_lshl_add_u64 v[74:75], s[12:13], 0, v[0:1]
	v_lshl_add_u64 v[76:77], s[14:15], 0, v[0:1]
	v_lshlrev_b32_e32 v152, 1, v152
	v_mov_b32_e32 v0, 0
	v_mad_i32_i24 v65, s61, v3, v65
	v_mad_i32_i24 v67, s61, v3, v67
	v_mad_i32_i24 v69, s61, v3, v69
	v_lshl_add_u64 v[78:79], s[16:17], 0, v[152:153]
	s_mov_b32 s19, s20
	v_mov_b32_e32 v1, v0
	v_mov_b32_e32 v2, v0
	v_mov_b32_e32 v3, v0
	v_mov_b32_e32 v4, v0
	v_mov_b32_e32 v5, v0
	v_mov_b32_e32 v6, v0
	v_mov_b32_e32 v7, v0
	v_mov_b32_e32 v8, v0
	v_mov_b32_e32 v9, v0
	v_mov_b32_e32 v10, v0
	v_mov_b32_e32 v11, v0
	v_mov_b32_e32 v12, v0
	v_mov_b32_e32 v13, v0
	v_mov_b32_e32 v14, v0
	v_mov_b32_e32 v15, v0
	v_mov_b32_e32 v16, v0
	v_mov_b32_e32 v17, v0
	v_mov_b32_e32 v18, v0
	v_mov_b32_e32 v19, v0
	v_mov_b32_e32 v20, v0
	v_mov_b32_e32 v21, v0
	v_mov_b32_e32 v22, v0
	v_mov_b32_e32 v23, v0
	v_mov_b32_e32 v24, v0
	v_mov_b32_e32 v25, v0
	v_mov_b32_e32 v26, v0
	v_mov_b32_e32 v27, v0
	v_mov_b32_e32 v36, v0
	v_mov_b32_e32 v37, v0
	v_mov_b32_e32 v38, v0
	v_mov_b32_e32 v39, v0
	v_mov_b32_e32 v28, v0
	v_mov_b32_e32 v29, v0
	v_mov_b32_e32 v30, v0
	v_mov_b32_e32 v31, v0
	v_mov_b32_e32 v32, v0
	v_mov_b32_e32 v33, v0
	v_mov_b32_e32 v34, v0
	v_mov_b32_e32 v35, v0
	v_mov_b32_e32 v40, v0
	v_mov_b32_e32 v41, v0
	v_mov_b32_e32 v42, v0
	v_mov_b32_e32 v43, v0
	v_mov_b32_e32 v44, v0
	v_mov_b32_e32 v45, v0
	v_mov_b32_e32 v46, v0
	v_mov_b32_e32 v47, v0
	v_mov_b32_e32 v48, v0
	v_mov_b32_e32 v49, v0
	v_mov_b32_e32 v50, v0
	v_mov_b32_e32 v51, v0
	v_mov_b32_e32 v52, v0
	v_mov_b32_e32 v53, v0
	v_mov_b32_e32 v54, v0
	v_mov_b32_e32 v55, v0
	v_mov_b32_e32 v56, v0
	v_mov_b32_e32 v57, v0
	v_mov_b32_e32 v58, v0
	v_mov_b32_e32 v59, v0
	v_mov_b32_e32 v60, v0
	v_mov_b32_e32 v61, v0
	v_mov_b32_e32 v62, v0
	v_mov_b32_e32 v63, v0
	v_lshl_add_u64 v[70:71], v[88:89], 1, v[70:71]
	v_lshl_add_u64 v[68:69], v[88:89], 1, v[68:69]
	v_lshl_add_u64 v[66:67], v[88:89], 1, v[66:67]
	v_lshl_add_u64 v[64:65], v[88:89], 1, v[64:65]
	v_lshl_add_u64 v[78:79], v[88:89], 1, v[78:79]
	v_lshl_add_u64 v[76:77], v[88:89], 1, v[76:77]
	v_lshl_add_u64 v[74:75], v[88:89], 1, v[74:75]
	v_lshl_add_u64 v[72:73], v[88:89], 1, v[72:73]
	v_mov_b32_e32 v250, 0x100
	v_mov_b32_e32 v251, 0
	global_load_dwordx4 v[80:83], v[70:71], off
	global_load_dwordx4 v[84:87], v[68:69], off
	global_load_dwordx4 v[90:93], v[66:67], off
	global_load_dwordx4 v[108:111], v[64:65], off
	global_load_dwordx4 v[112:115], v[78:79], off
	global_load_dwordx4 v[116:119], v[76:77], off
	global_load_dwordx4 v[120:123], v[74:75], off
	global_load_dwordx4 v[124:127], v[72:73], off
	global_load_dwordx4 v[128:131], v[70:71], off offset:16
	global_load_dwordx4 v[132:135], v[68:69], off offset:16
	global_load_dwordx4 v[136:139], v[66:67], off offset:16
	global_load_dwordx4 v[140:143], v[64:65], off offset:16
	global_load_dwordx4 v[144:147], v[78:79], off offset:16
	global_load_dwordx4 v[158:161], v[76:77], off offset:16
	global_load_dwordx4 v[162:165], v[74:75], off offset:16
	global_load_dwordx4 v[166:169], v[72:73], off offset:16
	global_load_dwordx4 v[170:173], v[70:71], off offset:128
	global_load_dwordx4 v[178:181], v[68:69], off offset:128
	global_load_dwordx4 v[194:197], v[66:67], off offset:128
	global_load_dwordx4 v[198:201], v[64:65], off offset:128
	global_load_dwordx4 v[202:205], v[78:79], off offset:128
	global_load_dwordx4 v[206:209], v[76:77], off offset:128
	global_load_dwordx4 v[210:213], v[74:75], off offset:128
	global_load_dwordx4 v[214:217], v[72:73], off offset:128
	global_load_dwordx4 v[218:221], v[70:71], off offset:144
	global_load_dwordx4 v[222:225], v[68:69], off offset:144
	global_load_dwordx4 v[226:229], v[66:67], off offset:144
	global_load_dwordx4 v[230:233], v[64:65], off offset:144
	global_load_dwordx4 v[234:237], v[78:79], off offset:144
	global_load_dwordx4 v[238:241], v[76:77], off offset:144
	global_load_dwordx4 v[242:245], v[74:75], off offset:144
	global_load_dwordx4 v[246:249], v[72:73], off offset:144
	s_lshr_b32 s19, s19, 2
	s_add_i32 s19, s19, -1
.Lgsa_loop:
	s_cmp_eq_u32 s19, 0
	s_cbranch_scc1 .Lgsa_tail
	s_waitcnt vmcnt(24)
	v_mfma_f32_16x16x32_bf16 v[36:39], v[80:83], v[112:115], v[36:39]
	v_mfma_f32_16x16x32_bf16 v[24:27], v[84:87], v[112:115], v[24:27]
	v_mfma_f32_16x16x32_bf16 v[20:23], v[90:93], v[112:115], v[20:23]
	v_mfma_f32_16x16x32_bf16 v[16:19], v[108:111], v[112:115], v[16:19]
	v_mfma_f32_16x16x32_bf16 v[12:15], v[80:83], v[116:119], v[12:15]
	v_mfma_f32_16x16x32_bf16 v[8:11], v[84:87], v[116:119], v[8:11]
	v_mfma_f32_16x16x32_bf16 v[4:7], v[90:93], v[116:119], v[4:7]
	v_mfma_f32_16x16x32_bf16 v[0:3], v[108:111], v[116:119], v[0:3]
	v_mfma_f32_16x16x32_bf16 v[28:31], v[80:83], v[120:123], v[28:31]
	v_mfma_f32_16x16x32_bf16 v[32:35], v[84:87], v[120:123], v[32:35]
	v_mfma_f32_16x16x32_bf16 v[40:43], v[90:93], v[120:123], v[40:43]
	v_mfma_f32_16x16x32_bf16 v[44:47], v[108:111], v[120:123], v[44:47]
	v_mfma_f32_16x16x32_bf16 v[48:51], v[80:83], v[124:127], v[48:51]
	v_mfma_f32_16x16x32_bf16 v[52:55], v[84:87], v[124:127], v[52:55]
	v_mfma_f32_16x16x32_bf16 v[56:59], v[90:93], v[124:127], v[56:59]
	v_mfma_f32_16x16x32_bf16 v[60:63], v[108:111], v[124:127], v[60:63]
	global_load_dwordx4 v[80:83], v[70:71], off offset:256
	global_load_dwordx4 v[84:87], v[68:69], off offset:256
	global_load_dwordx4 v[90:93], v[66:67], off offset:256
	global_load_dwordx4 v[108:111], v[64:65], off offset:256
	global_load_dwordx4 v[112:115], v[78:79], off offset:256
	global_load_dwordx4 v[116:119], v[76:77], off offset:256
	global_load_dwordx4 v[120:123], v[74:75], off offset:256
	global_load_dwordx4 v[124:127], v[72:73], off offset:256
	s_waitcnt vmcnt(24)
	v_mfma_f32_16x16x32_bf16 v[36:39], v[128:131], v[144:147], v[36:39]
	v_mfma_f32_16x16x32_bf16 v[24:27], v[132:135], v[144:147], v[24:27]
	v_mfma_f32_16x16x32_bf16 v[20:23], v[136:139], v[144:147], v[20:23]
	v_mfma_f32_16x16x32_bf16 v[16:19], v[140:143], v[144:147], v[16:19]
	v_mfma_f32_16x16x32_bf16 v[12:15], v[128:131], v[158:161], v[12:15]
	v_mfma_f32_16x16x32_bf16 v[8:11], v[132:135], v[158:161], v[8:11]
	v_mfma_f32_16x16x32_bf16 v[4:7], v[136:139], v[158:161], v[4:7]
	v_mfma_f32_16x16x32_bf16 v[0:3], v[140:143], v[158:161], v[0:3]
	v_mfma_f32_16x16x32_bf16 v[28:31], v[128:131], v[162:165], v[28:31]
	v_mfma_f32_16x16x32_bf16 v[32:35], v[132:135], v[162:165], v[32:35]
	v_mfma_f32_16x16x32_bf16 v[40:43], v[136:139], v[162:165], v[40:43]
	v_mfma_f32_16x16x32_bf16 v[44:47], v[140:143], v[162:165], v[44:47]
	v_mfma_f32_16x16x32_bf16 v[48:51], v[128:131], v[166:169], v[48:51]
	v_mfma_f32_16x16x32_bf16 v[52:55], v[132:135], v[166:169], v[52:55]
	v_mfma_f32_16x16x32_bf16 v[56:59], v[136:139], v[166:169], v[56:59]
	v_mfma_f32_16x16x32_bf16 v[60:63], v[140:143], v[166:169], v[60:63]
	global_load_dwordx4 v[128:131], v[70:71], off offset:272
	global_load_dwordx4 v[132:135], v[68:69], off offset:272
	global_load_dwordx4 v[136:139], v[66:67], off offset:272
	global_load_dwordx4 v[140:143], v[64:65], off offset:272
	global_load_dwordx4 v[144:147], v[78:79], off offset:272
	global_load_dwordx4 v[158:161], v[76:77], off offset:272
	global_load_dwordx4 v[162:165], v[74:75], off offset:272
	global_load_dwordx4 v[166:169], v[72:73], off offset:272
	s_waitcnt vmcnt(24)
	v_mfma_f32_16x16x32_bf16 v[36:39], v[170:173], v[202:205], v[36:39]
	v_mfma_f32_16x16x32_bf16 v[24:27], v[178:181], v[202:205], v[24:27]
	v_mfma_f32_16x16x32_bf16 v[20:23], v[194:197], v[202:205], v[20:23]
	v_mfma_f32_16x16x32_bf16 v[16:19], v[198:201], v[202:205], v[16:19]
	v_mfma_f32_16x16x32_bf16 v[12:15], v[170:173], v[206:209], v[12:15]
	v_mfma_f32_16x16x32_bf16 v[8:11], v[178:181], v[206:209], v[8:11]
	v_mfma_f32_16x16x32_bf16 v[4:7], v[194:197], v[206:209], v[4:7]
	v_mfma_f32_16x16x32_bf16 v[0:3], v[198:201], v[206:209], v[0:3]
	v_mfma_f32_16x16x32_bf16 v[28:31], v[170:173], v[210:213], v[28:31]
	v_mfma_f32_16x16x32_bf16 v[32:35], v[178:181], v[210:213], v[32:35]
	v_mfma_f32_16x16x32_bf16 v[40:43], v[194:197], v[210:213], v[40:43]
	v_mfma_f32_16x16x32_bf16 v[44:47], v[198:201], v[210:213], v[44:47]
	v_mfma_f32_16x16x32_bf16 v[48:51], v[170:173], v[214:217], v[48:51]
	v_mfma_f32_16x16x32_bf16 v[52:55], v[178:181], v[214:217], v[52:55]
	v_mfma_f32_16x16x32_bf16 v[56:59], v[194:197], v[214:217], v[56:59]
	v_mfma_f32_16x16x32_bf16 v[60:63], v[198:201], v[214:217], v[60:63]
	global_load_dwordx4 v[170:173], v[70:71], off offset:384
	global_load_dwordx4 v[178:181], v[68:69], off offset:384
	global_load_dwordx4 v[194:197], v[66:67], off offset:384
	global_load_dwordx4 v[198:201], v[64:65], off offset:384
	global_load_dwordx4 v[202:205], v[78:79], off offset:384
	global_load_dwordx4 v[206:209], v[76:77], off offset:384
	global_load_dwordx4 v[210:213], v[74:75], off offset:384
	global_load_dwordx4 v[214:217], v[72:73], off offset:384
	s_waitcnt vmcnt(24)
	v_mfma_f32_16x16x32_bf16 v[36:39], v[218:221], v[234:237], v[36:39]
	v_mfma_f32_16x16x32_bf16 v[24:27], v[222:225], v[234:237], v[24:27]
	v_mfma_f32_16x16x32_bf16 v[20:23], v[226:229], v[234:237], v[20:23]
	v_mfma_f32_16x16x32_bf16 v[16:19], v[230:233], v[234:237], v[16:19]
	v_mfma_f32_16x16x32_bf16 v[12:15], v[218:221], v[238:241], v[12:15]
	v_mfma_f32_16x16x32_bf16 v[8:11], v[222:225], v[238:241], v[8:11]
	v_mfma_f32_16x16x32_bf16 v[4:7], v[226:229], v[238:241], v[4:7]
	v_mfma_f32_16x16x32_bf16 v[0:3], v[230:233], v[238:241], v[0:3]
	v_mfma_f32_16x16x32_bf16 v[28:31], v[218:221], v[242:245], v[28:31]
	v_mfma_f32_16x16x32_bf16 v[32:35], v[222:225], v[242:245], v[32:35]
	v_mfma_f32_16x16x32_bf16 v[40:43], v[226:229], v[242:245], v[40:43]
	v_mfma_f32_16x16x32_bf16 v[44:47], v[230:233], v[242:245], v[44:47]
	v_mfma_f32_16x16x32_bf16 v[48:51], v[218:221], v[246:249], v[48:51]
	v_mfma_f32_16x16x32_bf16 v[52:55], v[222:225], v[246:249], v[52:55]
	v_mfma_f32_16x16x32_bf16 v[56:59], v[226:229], v[246:249], v[56:59]
	v_mfma_f32_16x16x32_bf16 v[60:63], v[230:233], v[246:249], v[60:63]
	global_load_dwordx4 v[218:221], v[70:71], off offset:400
	global_load_dwordx4 v[222:225], v[68:69], off offset:400
	global_load_dwordx4 v[226:229], v[66:67], off offset:400
	global_load_dwordx4 v[230:233], v[64:65], off offset:400
	global_load_dwordx4 v[234:237], v[78:79], off offset:400
	global_load_dwordx4 v[238:241], v[76:77], off offset:400
	global_load_dwordx4 v[242:245], v[74:75], off offset:400
	global_load_dwordx4 v[246:249], v[72:73], off offset:400
	v_lshl_add_u64 v[70:71], v[70:71], 0, v[250:251]
	v_lshl_add_u64 v[68:69], v[68:69], 0, v[250:251]
	v_lshl_add_u64 v[66:67], v[66:67], 0, v[250:251]
	v_lshl_add_u64 v[64:65], v[64:65], 0, v[250:251]
	v_lshl_add_u64 v[78:79], v[78:79], 0, v[250:251]
	v_lshl_add_u64 v[76:77], v[76:77], 0, v[250:251]
	v_lshl_add_u64 v[74:75], v[74:75], 0, v[250:251]
	v_lshl_add_u64 v[72:73], v[72:73], 0, v[250:251]
	s_add_i32 s19, s19, -1
	s_branch .Lgsa_loop

.LBB0_744:
	s_and_b32 s22, s25, 0xffffffc0
	v_or_b32_e32 v2, s22, v193
	v_lshlrev_b32_e32 v4, 1, v2
	v_or_b32_e32 v5, 0x60, v4
	s_waitcnt lgkmcnt(0)
	v_mov_b64_e32 v[0:1], s[10:11]
	v_mad_u64_u32 v[64:65], s[22:23], s61, v5, v[0:1]
	v_or_b32_e32 v5, 64, v4
	v_or_b32_e32 v4, 32, v4
	v_mad_u64_u32 v[66:67], s[22:23], s61, v5, v[0:1]
	v_mad_u64_u32 v[68:69], s[22:23], s61, v4, v[0:1]
	v_mad_i64_i32 v[70:71], s[22:23], s24, v2, v[0:1]
	s_lshl_b32 s22, s52, 6
	s_and_b32 s22, s22, 0x3c0
	v_or_b32_e32 v0, s22, v193
	v_mul_u32_u24_e32 v152, s61, v0
	v_lshl_add_u64 v[0:1], s[8:9], 0, v[152:153]
	v_lshlrev_b64 v[0:1], 1, v[0:1]
	v_ashrrev_i32_e32 v3, 31, v2
	v_lshl_add_u64 v[72:73], s[14:15], 0, v[0:1]
	v_lshl_add_u64 v[74:75], s[16:17], 0, v[0:1]
	v_lshl_add_u64 v[76:77], s[18:19], 0, v[0:1]
	v_lshlrev_b32_e32 v152, 1, v152
	v_mov_b32_e32 v0, 0
	v_mad_i32_i24 v65, s61, v3, v65
	v_mad_i32_i24 v67, s61, v3, v67
	v_mad_i32_i24 v69, s61, v3, v69
	v_lshl_add_u64 v[78:79], s[20:21], 0, v[152:153]
	s_mov_b32 s23, s0
	v_mov_b32_e32 v1, v0
	v_mov_b32_e32 v2, v0
	v_mov_b32_e32 v3, v0
	v_mov_b32_e32 v4, v0
	v_mov_b32_e32 v5, v0
	v_mov_b32_e32 v6, v0
	v_mov_b32_e32 v7, v0
	v_mov_b32_e32 v8, v0
	v_mov_b32_e32 v9, v0
	v_mov_b32_e32 v10, v0
	v_mov_b32_e32 v11, v0
	v_mov_b32_e32 v12, v0
	v_mov_b32_e32 v13, v0
	v_mov_b32_e32 v14, v0
	v_mov_b32_e32 v15, v0
	v_mov_b32_e32 v16, v0
	v_mov_b32_e32 v17, v0
	v_mov_b32_e32 v18, v0
	v_mov_b32_e32 v19, v0
	v_mov_b32_e32 v20, v0
	v_mov_b32_e32 v21, v0
	v_mov_b32_e32 v22, v0
	v_mov_b32_e32 v23, v0
	v_mov_b32_e32 v24, v0
	v_mov_b32_e32 v25, v0
	v_mov_b32_e32 v26, v0
	v_mov_b32_e32 v27, v0
	v_mov_b32_e32 v36, v0
	v_mov_b32_e32 v37, v0
	v_mov_b32_e32 v38, v0
	v_mov_b32_e32 v39, v0
	v_mov_b32_e32 v28, v0
	v_mov_b32_e32 v29, v0
	v_mov_b32_e32 v30, v0
	v_mov_b32_e32 v31, v0
	v_mov_b32_e32 v32, v0
	v_mov_b32_e32 v33, v0
	v_mov_b32_e32 v34, v0
	v_mov_b32_e32 v35, v0
	v_mov_b32_e32 v40, v0
	v_mov_b32_e32 v41, v0
	v_mov_b32_e32 v42, v0
	v_mov_b32_e32 v43, v0
	v_mov_b32_e32 v44, v0
	v_mov_b32_e32 v45, v0
	v_mov_b32_e32 v46, v0
	v_mov_b32_e32 v47, v0
	v_mov_b32_e32 v48, v0
	v_mov_b32_e32 v49, v0
	v_mov_b32_e32 v50, v0
	v_mov_b32_e32 v51, v0
	v_mov_b32_e32 v52, v0
	v_mov_b32_e32 v53, v0
	v_mov_b32_e32 v54, v0
	v_mov_b32_e32 v55, v0
	v_mov_b32_e32 v56, v0
	v_mov_b32_e32 v57, v0
	v_mov_b32_e32 v58, v0
	v_mov_b32_e32 v59, v0
	v_mov_b32_e32 v60, v0
	v_mov_b32_e32 v61, v0
	v_mov_b32_e32 v62, v0
	v_mov_b32_e32 v63, v0
	v_lshl_add_u64 v[70:71], v[80:81], 1, v[70:71]
	v_lshl_add_u64 v[68:69], v[80:81], 1, v[68:69]
	v_lshl_add_u64 v[66:67], v[80:81], 1, v[66:67]
	v_lshl_add_u64 v[64:65], v[80:81], 1, v[64:65]
	v_lshl_add_u64 v[78:79], v[80:81], 1, v[78:79]
	v_lshl_add_u64 v[76:77], v[80:81], 1, v[76:77]
	v_lshl_add_u64 v[74:75], v[80:81], 1, v[74:75]
	v_lshl_add_u64 v[72:73], v[80:81], 1, v[72:73]
	v_mov_b32_e32 v250, 0x100
	v_mov_b32_e32 v251, 0
	global_load_dwordx4 v[82:85], v[70:71], off
	global_load_dwordx4 v[104:107], v[68:69], off
	global_load_dwordx4 v[108:111], v[66:67], off
	global_load_dwordx4 v[112:115], v[64:65], off
	global_load_dwordx4 v[116:119], v[78:79], off
	global_load_dwordx4 v[120:123], v[76:77], off
	global_load_dwordx4 v[124:127], v[74:75], off
	global_load_dwordx4 v[128:131], v[72:73], off
	global_load_dwordx4 v[132:135], v[70:71], off offset:16
	global_load_dwordx4 v[136:139], v[68:69], off offset:16
	global_load_dwordx4 v[140:143], v[66:67], off offset:16
	global_load_dwordx4 v[144:147], v[64:65], off offset:16
	global_load_dwordx4 v[158:161], v[78:79], off offset:16
	global_load_dwordx4 v[162:165], v[76:77], off offset:16
	global_load_dwordx4 v[166:169], v[74:75], off offset:16
	global_load_dwordx4 v[170:173], v[72:73], off offset:16
	global_load_dwordx4 v[174:177], v[70:71], off offset:128
	global_load_dwordx4 v[178:181], v[68:69], off offset:128
	global_load_dwordx4 v[194:197], v[66:67], off offset:128
	global_load_dwordx4 v[198:201], v[64:65], off offset:128
	global_load_dwordx4 v[202:205], v[78:79], off offset:128
	global_load_dwordx4 v[206:209], v[76:77], off offset:128
	global_load_dwordx4 v[210:213], v[74:75], off offset:128
	global_load_dwordx4 v[214:217], v[72:73], off offset:128
	global_load_dwordx4 v[218:221], v[70:71], off offset:144
	global_load_dwordx4 v[222:225], v[68:69], off offset:144
	global_load_dwordx4 v[226:229], v[66:67], off offset:144
	global_load_dwordx4 v[230:233], v[64:65], off offset:144
	global_load_dwordx4 v[234:237], v[78:79], off offset:144
	global_load_dwordx4 v[238:241], v[76:77], off offset:144
	global_load_dwordx4 v[242:245], v[74:75], off offset:144
	global_load_dwordx4 v[246:249], v[72:73], off offset:144
	s_lshr_b32 s23, s23, 2
	s_add_i32 s23, s23, -1
.Lgsr_loop:
	s_cmp_eq_u32 s23, 0
	s_cbranch_scc1 .Lgsr_tail
	s_waitcnt vmcnt(24)
	v_mfma_f32_16x16x32_bf16 v[36:39], v[82:85], v[116:119], v[36:39]
	v_mfma_f32_16x16x32_bf16 v[24:27], v[104:107], v[116:119], v[24:27]
	v_mfma_f32_16x16x32_bf16 v[20:23], v[108:111], v[116:119], v[20:23]
	v_mfma_f32_16x16x32_bf16 v[16:19], v[112:115], v[116:119], v[16:19]
	v_mfma_f32_16x16x32_bf16 v[12:15], v[82:85], v[120:123], v[12:15]
	v_mfma_f32_16x16x32_bf16 v[8:11], v[104:107], v[120:123], v[8:11]
	v_mfma_f32_16x16x32_bf16 v[4:7], v[108:111], v[120:123], v[4:7]
	v_mfma_f32_16x16x32_bf16 v[0:3], v[112:115], v[120:123], v[0:3]
	v_mfma_f32_16x16x32_bf16 v[28:31], v[82:85], v[124:127], v[28:31]
	v_mfma_f32_16x16x32_bf16 v[32:35], v[104:107], v[124:127], v[32:35]
	v_mfma_f32_16x16x32_bf16 v[40:43], v[108:111], v[124:127], v[40:43]
	v_mfma_f32_16x16x32_bf16 v[44:47], v[112:115], v[124:127], v[44:47]
	v_mfma_f32_16x16x32_bf16 v[48:51], v[82:85], v[128:131], v[48:51]
	v_mfma_f32_16x16x32_bf16 v[52:55], v[104:107], v[128:131], v[52:55]
	v_mfma_f32_16x16x32_bf16 v[56:59], v[108:111], v[128:131], v[56:59]
	v_mfma_f32_16x16x32_bf16 v[60:63], v[112:115], v[128:131], v[60:63]
	global_load_dwordx4 v[82:85], v[70:71], off offset:256
	global_load_dwordx4 v[104:107], v[68:69], off offset:256
	global_load_dwordx4 v[108:111], v[66:67], off offset:256
	global_load_dwordx4 v[112:115], v[64:65], off offset:256
	global_load_dwordx4 v[116:119], v[78:79], off offset:256
	global_load_dwordx4 v[120:123], v[76:77], off offset:256
	global_load_dwordx4 v[124:127], v[74:75], off offset:256
	global_load_dwordx4 v[128:131], v[72:73], off offset:256
	s_waitcnt vmcnt(24)
	v_mfma_f32_16x16x32_bf16 v[36:39], v[132:135], v[158:161], v[36:39]
	v_mfma_f32_16x16x32_bf16 v[24:27], v[136:139], v[158:161], v[24:27]
	v_mfma_f32_16x16x32_bf16 v[20:23], v[140:143], v[158:161], v[20:23]
	v_mfma_f32_16x16x32_bf16 v[16:19], v[144:147], v[158:161], v[16:19]
	v_mfma_f32_16x16x32_bf16 v[12:15], v[132:135], v[162:165], v[12:15]
	v_mfma_f32_16x16x32_bf16 v[8:11], v[136:139], v[162:165], v[8:11]
	v_mfma_f32_16x16x32_bf16 v[4:7], v[140:143], v[162:165], v[4:7]
	v_mfma_f32_16x16x32_bf16 v[0:3], v[144:147], v[162:165], v[0:3]
	v_mfma_f32_16x16x32_bf16 v[28:31], v[132:135], v[166:169], v[28:31]
	v_mfma_f32_16x16x32_bf16 v[32:35], v[136:139], v[166:169], v[32:35]
	v_mfma_f32_16x16x32_bf16 v[40:43], v[140:143], v[166:169], v[40:43]
	v_mfma_f32_16x16x32_bf16 v[44:47], v[144:147], v[166:169], v[44:47]
	v_mfma_f32_16x16x32_bf16 v[48:51], v[132:135], v[170:173], v[48:51]
	v_mfma_f32_16x16x32_bf16 v[52:55], v[136:139], v[170:173], v[52:55]
	v_mfma_f32_16x16x32_bf16 v[56:59], v[140:143], v[170:173], v[56:59]
	v_mfma_f32_16x16x32_bf16 v[60:63], v[144:147], v[170:173], v[60:63]
	global_load_dwordx4 v[132:135], v[70:71], off offset:272
	global_load_dwordx4 v[136:139], v[68:69], off offset:272
	global_load_dwordx4 v[140:143], v[66:67], off offset:272
	global_load_dwordx4 v[144:147], v[64:65], off offset:272
	global_load_dwordx4 v[158:161], v[78:79], off offset:272
	global_load_dwordx4 v[162:165], v[76:77], off offset:272
	global_load_dwordx4 v[166:169], v[74:75], off offset:272
	global_load_dwordx4 v[170:173], v[72:73], off offset:272
	s_waitcnt vmcnt(24)
	v_mfma_f32_16x16x32_bf16 v[36:39], v[174:177], v[202:205], v[36:39]
	v_mfma_f32_16x16x32_bf16 v[24:27], v[178:181], v[202:205], v[24:27]
	v_mfma_f32_16x16x32_bf16 v[20:23], v[194:197], v[202:205], v[20:23]
	v_mfma_f32_16x16x32_bf16 v[16:19], v[198:201], v[202:205], v[16:19]
	v_mfma_f32_16x16x32_bf16 v[12:15], v[174:177], v[206:209], v[12:15]
	v_mfma_f32_16x16x32_bf16 v[8:11], v[178:181], v[206:209], v[8:11]
	v_mfma_f32_16x16x32_bf16 v[4:7], v[194:197], v[206:209], v[4:7]
	v_mfma_f32_16x16x32_bf16 v[0:3], v[198:201], v[206:209], v[0:3]
	v_mfma_f32_16x16x32_bf16 v[28:31], v[174:177], v[210:213], v[28:31]
	v_mfma_f32_16x16x32_bf16 v[32:35], v[178:181], v[210:213], v[32:35]
	v_mfma_f32_16x16x32_bf16 v[40:43], v[194:197], v[210:213], v[40:43]
	v_mfma_f32_16x16x32_bf16 v[44:47], v[198:201], v[210:213], v[44:47]
	v_mfma_f32_16x16x32_bf16 v[48:51], v[174:177], v[214:217], v[48:51]
	v_mfma_f32_16x16x32_bf16 v[52:55], v[178:181], v[214:217], v[52:55]
	v_mfma_f32_16x16x32_bf16 v[56:59], v[194:197], v[214:217], v[56:59]
	v_mfma_f32_16x16x32_bf16 v[60:63], v[198:201], v[214:217], v[60:63]
	global_load_dwordx4 v[174:177], v[70:71], off offset:384
	global_load_dwordx4 v[178:181], v[68:69], off offset:384
	global_load_dwordx4 v[194:197], v[66:67], off offset:384
	global_load_dwordx4 v[198:201], v[64:65], off offset:384
	global_load_dwordx4 v[202:205], v[78:79], off offset:384
	global_load_dwordx4 v[206:209], v[76:77], off offset:384
	global_load_dwordx4 v[210:213], v[74:75], off offset:384
	global_load_dwordx4 v[214:217], v[72:73], off offset:384
	s_waitcnt vmcnt(24)
	v_mfma_f32_16x16x32_bf16 v[36:39], v[218:221], v[234:237], v[36:39]
	v_mfma_f32_16x16x32_bf16 v[24:27], v[222:225], v[234:237], v[24:27]
	v_mfma_f32_16x16x32_bf16 v[20:23], v[226:229], v[234:237], v[20:23]
	v_mfma_f32_16x16x32_bf16 v[16:19], v[230:233], v[234:237], v[16:19]
	v_mfma_f32_16x16x32_bf16 v[12:15], v[218:221], v[238:241], v[12:15]
	v_mfma_f32_16x16x32_bf16 v[8:11], v[222:225], v[238:241], v[8:11]
	v_mfma_f32_16x16x32_bf16 v[4:7], v[226:229], v[238:241], v[4:7]
	v_mfma_f32_16x16x32_bf16 v[0:3], v[230:233], v[238:241], v[0:3]
	v_mfma_f32_16x16x32_bf16 v[28:31], v[218:221], v[242:245], v[28:31]
	v_mfma_f32_16x16x32_bf16 v[32:35], v[222:225], v[242:245], v[32:35]
	v_mfma_f32_16x16x32_bf16 v[40:43], v[226:229], v[242:245], v[40:43]
	v_mfma_f32_16x16x32_bf16 v[44:47], v[230:233], v[242:245], v[44:47]
	v_mfma_f32_16x16x32_bf16 v[48:51], v[218:221], v[246:249], v[48:51]
	v_mfma_f32_16x16x32_bf16 v[52:55], v[222:225], v[246:249], v[52:55]
	v_mfma_f32_16x16x32_bf16 v[56:59], v[226:229], v[246:249], v[56:59]
	v_mfma_f32_16x16x32_bf16 v[60:63], v[230:233], v[246:249], v[60:63]
	global_load_dwordx4 v[218:221], v[70:71], off offset:400
	global_load_dwordx4 v[222:225], v[68:69], off offset:400
	global_load_dwordx4 v[226:229], v[66:67], off offset:400
	global_load_dwordx4 v[230:233], v[64:65], off offset:400
	global_load_dwordx4 v[234:237], v[78:79], off offset:400
	global_load_dwordx4 v[238:241], v[76:77], off offset:400
	global_load_dwordx4 v[242:245], v[74:75], off offset:400
	global_load_dwordx4 v[246:249], v[72:73], off offset:400
	v_lshl_add_u64 v[70:71], v[70:71], 0, v[250:251]
	v_lshl_add_u64 v[68:69], v[68:69], 0, v[250:251]
	v_lshl_add_u64 v[66:67], v[66:67], 0, v[250:251]
	v_lshl_add_u64 v[64:65], v[64:65], 0, v[250:251]
	v_lshl_add_u64 v[78:79], v[78:79], 0, v[250:251]
	v_lshl_add_u64 v[76:77], v[76:77], 0, v[250:251]
	v_lshl_add_u64 v[74:75], v[74:75], 0, v[250:251]
	v_lshl_add_u64 v[72:73], v[72:73], 0, v[250:251]
	s_add_i32 s23, s23, -1
	s_branch .Lgsr_loop
